# M3 dno units: the early vmcnt(0) that only served the unpack of the first O0 piece is gone (unpack moved behind the unit's load barrier), so each unit has one load round trip instead of two
# speedup vs baseline: 1.0061x; 1.0004x over previous
.LBB0_916:
	s_or_b64 exec, exec, s[20:21]
	s_ashr_i32 s19, s18, 31
	s_lshl_b64 s[2:3], s[18:19], 15
	s_add_u32 s2, s26, s2
	s_addc_u32 s3, s27, s3
	v_lshlrev_b32_e32 v1, 1, v13
	v_and_b32_e32 v2, 3, v0
	s_lshl_b32 s6, s35, 5
	v_and_b32_e32 v3, 8, v0
	v_lshrrev_b32_e32 v15, 5, v39
	v_or3_b32 v3, s6, v3, v15
	v_and_b32_e32 v15, 16, v0
	v_and_or_b32 v1, v1, 8, v2
	v_lshl_or_b32 v1, v1, 5, v15
	v_lshlrev_b32_e32 v15, 9, v3
	v_or_b32_e32 v2, v15, v1
	v_ashrrev_i32_e32 v3, 31, v2
	v_lshl_add_u64 v[18:19], s[2:3], 0, v[2:3]
	v_or_b32_e32 v17, 0x2000, v15
	global_load_dwordx4 v[42:45], v[18:19], off
	v_or_b32_e32 v18, v17, v1
	v_ashrrev_i32_e32 v19, 31, v18
	v_or_b32_e32 v22, 0x80, v1
	v_lshl_add_u64 v[18:19], s[2:3], 0, v[18:19]
	global_load_dwordx4 v[50:53], v[18:19], off
	v_or_b32_e32 v18, v17, v22
	v_ashrrev_i32_e32 v19, 31, v18
	v_lshl_add_u64 v[18:19], s[2:3], 0, v[18:19]
	v_ashrrev_i32_e32 v3, 31, v15
	global_load_dwordx4 v[54:57], v[18:19], off
	v_or_b32_e32 v18, v15, v22
	s_nop 0
	v_lshl_add_u64 v[2:3], s[2:3], 0, v[2:3]
	v_ashrrev_i32_e32 v19, 31, v18
	v_or_b32_e32 v114, 0x2400, v15
	global_load_dwordx4 v[46:49], v[2:3], off offset:128
	global_load_dwordx4 v[58:61], v[2:3], off offset:1024
	v_lshl_add_u64 v[20:21], s[2:3], 0, v[18:19]
	v_or_b32_e32 v18, v114, v1
	v_ashrrev_i32_e32 v19, 31, v18
	v_lshl_add_u64 v[18:19], s[2:3], 0, v[18:19]
	global_load_dwordx4 v[62:65], v[2:3], off offset:3072
	global_load_dwordx4 v[66:69], v[20:21], off offset:1024
	global_load_dwordx4 v[70:73], v[18:19], off
	global_load_dwordx4 v[78:81], v[2:3], off offset:2048
	v_or_b32_e32 v18, v114, v22
	v_ashrrev_i32_e32 v19, 31, v18
	v_lshl_add_u64 v[18:19], s[2:3], 0, v[18:19]
	global_load_dwordx4 v[74:77], v[18:19], off
	global_load_dwordx4 v[94:97], v[20:21], off offset:3072
	v_or_b32_e32 v115, 0x2800, v15
	v_or_b32_e32 v2, v115, v1
	global_load_dwordx4 v[82:85], v[20:21], off offset:2048
	v_ashrrev_i32_e32 v3, 31, v2
	v_lshl_add_u64 v[2:3], s[2:3], 0, v[2:3]
	global_load_dwordx4 v[86:89], v[2:3], off
	v_or_b32_e32 v2, v115, v22
	v_or_b32_e32 v115, 0x2c00, v15
	v_or_b32_e32 v20, v115, v1
	v_ashrrev_i32_e32 v3, 31, v2
	v_ashrrev_i32_e32 v21, 31, v20
	v_lshl_add_u64 v[2:3], s[2:3], 0, v[2:3]
	v_lshl_add_u64 v[20:21], s[2:3], 0, v[20:21]
	global_load_dwordx4 v[90:93], v[2:3], off
	global_load_dwordx4 v[98:101], v[20:21], off
	v_or_b32_e32 v20, v115, v22
	v_ashrrev_i32_e32 v21, 31, v20
	v_lshl_add_u64 v[20:21], s[2:3], 0, v[20:21]
	global_load_dwordx4 v[102:105], v[20:21], off
	v_mad_i64_i32 v[2:3], s[18:19], v28, s28, v[26:27]
	s_lshl_b32 s6, s34, 8
	s_lshl_b32 s18, s35, 6
	v_lshrrev_b32_e32 v0, 1, v0
	v_lshl_add_u64 v[2:3], v[2:3], 0, s[6:7]
	s_ashr_i32 s19, s18, 31
	v_and_b32_e32 v41, 24, v0
	v_lshl_add_u64 v[2:3], s[18:19], 1, v[2:3]
	v_lshlrev_b32_e32 v24, 1, v41
	v_lshl_add_u64 v[0:1], v[2:3], 0, v[24:25]
	v_add_co_u32_e64 v108, s[2:3], s29, v0
	v_lshl_add_u64 v[106:107], v[0:1], 0, s[16:17]
	s_nop 0
	v_addc_co_u32_e64 v109, s[2:3], 0, v1, s[2:3]
	global_load_dwordx4 v[20:23], v[108:109], off offset:3072
	global_load_dwordx4 v[0:3], v[106:107], off offset:64
	v_lshlrev_b32_e32 v115, 4, v13
	v_and_b32_e32 v13, 0x70, v115
	v_add_u32_e32 v24, v31, v14
	s_waitcnt vmcnt(0) lgkmcnt(0)
	s_barrier
	v_lshlrev_b32_e32 v16, 16, v8
	v_and_b32_e32 v17, 0xffff0000, v8
	v_lshlrev_b32_e32 v18, 16, v9
	v_and_b32_e32 v19, 0xffff0000, v9
	v_lshlrev_b32_e32 v8, 16, v10
	v_and_b32_e32 v9, 0xffff0000, v10
	v_xad_u32 v10, v13, v12, v24
	ds_read_b128 v[106:109], v10 offset:32768
	v_or_b32_e32 v14, 64, v12
	v_xad_u32 v14, v13, v14, v24
	ds_read_b128 v[110:113], v14 offset:32768
	s_waitcnt lgkmcnt(0)
	v_mfma_f32_16x16x32_bf16 v[14:17], v[42:45], v[106:109], v[16:19]
	v_lshlrev_b32_e32 v10, 16, v11
	v_and_b32_e32 v11, 0xffff0000, v11
	s_nop 0
	v_or_b32_e32 v18, 0x80, v12
	v_xad_u32 v18, v13, v18, v24
	s_waitcnt vmcnt(14)
	v_mfma_f32_16x16x32_bf16 v[8:11], v[46:49], v[106:109], v[8:11]
	v_lshlrev_b32_e32 v42, 16, v4
	v_and_b32_e32 v43, 0xffff0000, v4
	v_lshlrev_b32_e32 v44, 16, v5
	v_and_b32_e32 v45, 0xffff0000, v5
	ds_read_b128 v[46:49], v18 offset:32768
	s_waitcnt vmcnt(13)
	v_mfma_f32_16x16x32_bf16 v[14:17], v[58:61], v[110:113], v[14:17]
	v_or_b32_e32 v12, 0xc0, v12
	v_xad_u32 v12, v13, v12, v24
	v_lshlrev_b32_e32 v4, 16, v6
	v_mfma_f32_16x16x32_bf16 v[42:45], v[50:53], v[106:109], v[42:45]
	v_and_b32_e32 v5, 0xffff0000, v6
	v_lshlrev_b32_e32 v6, 16, v7
	v_and_b32_e32 v7, 0xffff0000, v7
	s_waitcnt vmcnt(11)
	v_mfma_f32_16x16x32_bf16 v[8:11], v[66:69], v[110:113], v[8:11]
	ds_read_b128 v[50:53], v12 offset:32768
	v_cmp_gt_u32_e64 s[2:3], 16, v39
	v_mfma_f32_16x16x32_bf16 v[4:7], v[54:57], v[106:109], v[4:7]
	s_waitcnt vmcnt(10)
	v_mfma_f32_16x16x32_bf16 v[42:45], v[70:73], v[110:113], v[42:45]
	s_waitcnt vmcnt(9) lgkmcnt(1)
	v_mfma_f32_16x16x32_bf16 v[12:15], v[78:81], v[46:49], v[14:17]
	s_waitcnt vmcnt(6)
	v_mfma_f32_16x16x32_bf16 v[8:11], v[82:85], v[46:49], v[8:11]
	v_mfma_f32_16x16x32_bf16 v[4:7], v[74:77], v[110:113], v[4:7]
	s_waitcnt vmcnt(5)
	v_mfma_f32_16x16x32_bf16 v[42:45], v[86:89], v[46:49], v[42:45]
	s_waitcnt lgkmcnt(0)
	v_mfma_f32_16x16x32_bf16 v[16:19], v[62:65], v[50:53], v[12:15]
	v_mfma_f32_16x16x32_bf16 v[12:15], v[94:97], v[50:53], v[8:11]
	s_waitcnt vmcnt(4)
	v_mfma_f32_16x16x32_bf16 v[4:7], v[90:93], v[46:49], v[4:7]
	s_nop 4
	v_mul_f32_e32 v24, v17, v17
	v_fmac_f32_e32 v24, v16, v16
	s_waitcnt vmcnt(3)
	v_mfma_f32_16x16x32_bf16 v[8:11], v[98:101], v[50:53], v[42:45]
	s_nop 2
	v_mul_f32_e32 v42, v19, v19
	v_fmac_f32_e32 v42, v18, v18
	v_add_f32_e32 v24, v24, v42
	v_mul_f32_e32 v42, v13, v13
	v_mul_f32_e32 v43, v15, v15
	v_fmac_f32_e32 v42, v12, v12
	v_fmac_f32_e32 v43, v14, v14
	s_waitcnt vmcnt(2)
	v_mfma_f32_16x16x32_bf16 v[4:7], v[102:105], v[50:53], v[4:7]
	v_add_f32_e32 v42, v42, v43
	v_add_f32_e32 v24, v24, v42
	v_mul_f32_e32 v42, v9, v9
	v_mul_f32_e32 v43, v11, v11
	v_fmac_f32_e32 v42, v8, v8
	v_fmac_f32_e32 v43, v10, v10
	v_add_f32_e32 v42, v42, v43
	v_add_f32_e32 v24, v24, v42
	v_mul_f32_e32 v42, v5, v5
	v_mul_f32_e32 v43, v7, v7
	v_fmac_f32_e32 v42, v4, v4
	v_fmac_f32_e32 v43, v6, v6
	v_add_f32_e32 v42, v42, v43
	v_add_f32_e32 v24, v24, v42
	ds_bpermute_b32 v42, v36, v24
	s_waitcnt lgkmcnt(0)
	v_add_f32_e32 v42, v24, v42
	ds_bpermute_b32 v43, v37, v42
	v_lshlrev_b32_e32 v24, 3, v40
	s_and_saveexec_b64 s[20:21], s[2:3]
	s_cbranch_execz .LBB0_918
	s_lshl_b32 s2, s35, 2
	v_add3_u32 v39, v31, v24, s2
	s_waitcnt lgkmcnt(0)
	v_add_f32_e32 v40, v42, v43
	ds_write_b32 v39, v40 offset:49152
